# S2 scan: width-16 lane shifts (shfl_up/down 1,2,4,8) done with v_mov_b32_dpp row_shr/row_shl instead of ds_bpermute; on top of v50
# speedup vs baseline: 1.0024x; 1.0024x over previous
; __device__ __forceinline__ void lane_scan8(const u32x4 p0, const u32x4 p1, int d, float (&hl)[8], float (&pl)[8]) {
; __device__ __forceinline__ void scan_final(const Args& a, int gw, int ngw, int lane, int layer) {
;     ...
;     for (int it = 0; it < nmine; ++it) {
;         const bool tail = split && it * ngw >= full;
;         const int wt = tail ? full + (gw >> 1) : it * ngw + gw, eh0 = tail ? (gw & 1) : 0, eh1 = tail ? eh0 + 1 : 2;
;         const int chunk = S2REV ? NCHUNK - 1 - (wt >> 5) : chunk0 + (wt >> 5), c8 = (wt & 31) * 32 + g * 8;
;         const int row0 = chunk * 128 + 8 * j;
;         const float cv = CY[((size_t)(j >> 3) * NCHUNK + chunk) * 1024 + c8 + (j & 7)];
; #pragma unroll 1
;         for (int eh = eh0; eh < eh1; ++eh) {
;             const int c4 = c8 + eh * 4;
;             u32x4 lw[2][4], uw[2][4]; u32x2 rgw[8];
; #pragma unroll
;             for (int d = 0; d < 2; ++d)
; #pragma unroll
;                 for (int e = 0; e < 4; ++e) { const size_t off = ((size_t)d * 1024 + c4 + e) * MT + row0; lw[d][e] = *(const u32x4*)(LU + off); uw[d][e] = *(const u32x4*)(LU + off + 4); }
; #pragma unroll
;             for (int k = 0; k < 8; ++k) rgw[k] = *(const u32x2*)(ZT + zt(row0 + k, 1024 + c4));
;             float acc[8][4];
; #pragma unroll
;             for (int e = 0; e < 4; ++e) {
; #pragma unroll
;                 for (int d = 0; d < 2; ++d) {
;                     float hl[8], pl[8]; lane_scan8(lw[d][e], uw[d][e], d, hl, pl);
;                     float Pi = d == 0 ? pl[7] : pl[0], Hi = d == 0 ? hl[7] : hl[0];
; #pragma unroll
;                     for (int sft = 1; sft < 16; sft <<= 1) {
;                         const float Pp = d == 0 ? __shfl_up(Pi, sft, 16) : __shfl_down(Pi, sft, 16), Hp = d == 0 ? __shfl_up(Hi, sft, 16) : __shfl_down(Hi, sft, 16);
;                         const bool has = d == 0 ? (j >= sft) : (j + sft <= 15);
;                         if (has) { Hi = Pi * Hp + Hi; Pi = Pi * Pp; }
;                     }
;                     float Pe = d == 0 ? __shfl_up(Pi, 1, 16) : __shfl_down(Pi, 1, 16), He = d == 0 ? __shfl_up(Hi, 1, 16) : __shfl_down(Hi, 1, 16);
;                     if (d == 0 ? (j == 0) : (j == 15)) { Pe = 1.f; He = 0.f; }
;                     const float c0 = __shfl(cv, eh * 4 + e + 8 * d, 16);
.LBB0_1189:
	s_lshl_b32 s1, s52, 2
	v_add_u32_e32 v106, s1, v178
	v_or_b32_e32 v2, 1, v106
	v_mad_u64_u32 v[2:3], s[2:3], v2, s4, v[70:71]
	global_load_dwordx4 v[14:17], v[2:3], off offset:16
	global_load_dwordx4 v[30:33], v[2:3], off
	v_or_b32_e32 v2, 2, v106
	v_mad_u64_u32 v[6:7], s[2:3], v2, s4, v[70:71]
	global_load_dwordx4 v[2:5], v[6:7], off offset:16
	global_load_dwordx4 v[18:21], v[6:7], off
	v_or_b32_e32 v6, 3, v106
	v_mad_u64_u32 v[10:11], s[2:3], v6, s4, v[70:71]
	v_add_u32_e32 v12, 0x400, v106
	global_load_dwordx4 v[6:9], v[10:11], off offset:16
	global_load_dwordx4 v[22:25], v[10:11], off
	v_mad_u64_u32 v[10:11], s[2:3], v12, s4, v[70:71]
	global_load_dwordx4 v[58:61], v[10:11], off offset:16
	global_load_dwordx4 v[50:53], v[10:11], off
	v_add_u32_e32 v10, 0x401, v106
	v_mad_u64_u32 v[10:11], s[2:3], v10, s4, v[70:71]
	global_load_dwordx4 v[62:65], v[10:11], off offset:16
	global_load_dwordx4 v[54:57], v[10:11], off
	v_add_u32_e32 v10, 0x402, v106
	v_mad_u64_u32 v[10:11], s[2:3], v10, s4, v[70:71]
	global_load_dwordx4 v[42:45], v[10:11], off offset:16
	global_load_dwordx4 v[34:37], v[10:11], off
	v_add_u32_e32 v10, 0x403, v106
	v_mad_u64_u32 v[10:11], s[2:3], v10, s4, v[70:71]
	global_load_dwordx4 v[46:49], v[10:11], off offset:16
	global_load_dwordx4 v[38:41], v[10:11], off
	v_lshrrev_b32_e32 v10, 8, v12
	v_mul_u32_u24_e32 v174, 0x840000, v10
	v_and_b32_e32 v12, 0xfc, v106
	v_lshl_add_u64 v[10:11], v[174:175], 1, s[56:57]
	v_lshlrev_b32_e32 v174, 1, v12
	v_lshl_add_u64 v[10:11], v[10:11], 0, v[174:175]
	v_lshl_add_u64 v[12:13], v[10:11], 0, v[72:73]
	global_load_dwordx2 v[182:183], v[12:13], off
	v_lshl_add_u64 v[12:13], v[10:11], 0, v[74:75]
	global_load_dwordx2 v[152:153], v[12:13], off
	v_lshl_add_u64 v[12:13], v[10:11], 0, v[76:77]
	global_load_dwordx2 v[142:143], v[12:13], off
	v_lshl_add_u64 v[12:13], v[10:11], 0, v[78:79]
	global_load_dwordx2 v[136:137], v[12:13], off
	v_lshl_add_u64 v[12:13], v[10:11], 0, v[80:81]
	global_load_dwordx2 v[132:133], v[12:13], off
	v_lshl_add_u64 v[12:13], v[10:11], 0, v[82:83]
	global_load_dwordx2 v[128:129], v[12:13], off
	v_lshl_add_u64 v[12:13], v[10:11], 0, v[84:85]
	v_lshl_add_u64 v[10:11], v[10:11], 0, v[86:87]
	s_waitcnt vmcnt(22)
	v_mad_u64_u32 v[26:27], s[2:3], v106, s4, v[70:71]
	global_load_dwordx2 v[120:121], v[12:13], off
	global_load_dwordx2 v[104:105], v[10:11], off
	s_nop 0
	global_load_dwordx4 v[10:13], v[26:27], off offset:16
	s_nop 0
	global_load_dwordx4 v[26:29], v[26:27], off
	v_lshlrev_b32_e32 v174, 1, v106
	s_cmp_ge_u32 s52, s53
	s_mov_b32 s52, 1
	s_waitcnt vmcnt(22)
	v_and_b32_e32 v149, 0xffff0000, v30
	s_waitcnt vmcnt(17)
	v_and_b32_e32 v150, 0xffff0000, v61
	s_waitcnt vmcnt(16)
	v_and_b32_e32 v190, 0xffff0000, v53
	v_and_b32_e32 v180, 0xffff0000, v59
	s_waitcnt vmcnt(15)
	v_and_b32_e32 v151, 0xffff0000, v65
	v_and_b32_e32 v181, 0xffff0000, v63
	s_waitcnt vmcnt(14)
	v_and_b32_e32 v191, 0xffff0000, v57
	s_waitcnt vmcnt(12)
	v_and_b32_e32 v220, 0xffff0000, v37
	s_waitcnt vmcnt(10)
	v_and_b32_e32 v221, 0xffff0000, v41
	s_waitcnt vmcnt(0)
	v_lshlrev_b32_e32 v107, 16, v26
	v_exp_f32_e32 v110, v107
	v_lshlrev_b32_e32 v107, 16, v27
	v_exp_f32_e32 v156, v107
	v_lshlrev_b32_e32 v107, 16, v28
	v_exp_f32_e32 v146, v107
	v_lshlrev_b32_e32 v107, 16, v29
	v_exp_f32_e32 v140, v107
	v_lshlrev_b32_e32 v107, 16, v10
	v_exp_f32_e32 v134, v107
	v_lshlrev_b32_e32 v107, 16, v11
	v_exp_f32_e32 v130, v107
	v_lshlrev_b32_e32 v107, 16, v12
	v_exp_f32_e32 v122, v107
	v_lshlrev_b32_e32 v107, 16, v13
	v_exp_f32_e32 v116, v107
	v_add_lshl_u32 v107, s1, v225, 2
	ds_bpermute_b32 v124, v107, v69
	v_lshlrev_b32_e32 v107, 16, v50
	v_exp_f32_e32 v160, v107
	v_lshlrev_b32_e32 v107, 16, v51
	v_exp_f32_e32 v162, v107
	v_lshlrev_b32_e32 v107, 16, v52
	v_exp_f32_e32 v170, v107
	v_lshlrev_b32_e32 v107, 16, v53
	v_add_lshl_u32 v53, s1, v242, 2
	ds_bpermute_b32 v192, v53, v69
	v_lshlrev_b32_e32 v53, 16, v30
	v_exp_f32_e32 v111, v53
	v_lshlrev_b32_e32 v53, 16, v31
	v_exp_f32_e32 v157, v53
	v_lshlrev_b32_e32 v53, 16, v32
	v_exp_f32_e32 v147, v53
	v_lshlrev_b32_e32 v53, 16, v33
	v_exp_f32_e32 v141, v53
	v_lshlrev_b32_e32 v53, 16, v14
	v_exp_f32_e32 v135, v53
	v_lshlrev_b32_e32 v53, 16, v15
	v_exp_f32_e32 v131, v53
	v_lshlrev_b32_e32 v53, 16, v16
	v_exp_f32_e32 v123, v53
	v_lshlrev_b32_e32 v53, 16, v17
	v_exp_f32_e32 v117, v53
	v_add_lshl_u32 v53, s1, v239, 2
	ds_bpermute_b32 v125, v53, v69
	v_lshlrev_b32_e32 v53, 16, v54
	v_exp_f32_e32 v161, v53
	v_lshlrev_b32_e32 v53, 16, v55
	v_exp_f32_e32 v163, v53
	v_lshlrev_b32_e32 v53, 16, v56
	v_exp_f32_e32 v171, v53
	v_lshlrev_b32_e32 v53, 16, v57
	v_exp_f32_e32 v173, v53
	v_lshlrev_b32_e32 v53, 16, v62
	v_exp_f32_e32 v187, v53
	v_lshlrev_b32_e32 v53, 16, v63
	v_exp_f32_e32 v167, v53
	v_lshlrev_b32_e32 v53, 16, v65
	v_exp_f32_e32 v127, v53
	v_lshlrev_b32_e32 v53, 16, v64
	v_exp_f32_e32 v165, v53
	v_add_lshl_u32 v53, s1, v243, 2
	ds_bpermute_b32 v193, v53, v69
	v_lshlrev_b32_e32 v53, 16, v18
	v_exp_f32_e32 v108, v53
	v_lshlrev_b32_e32 v53, 16, v19
	v_exp_f32_e32 v188, v53
	v_lshlrev_b32_e32 v53, 16, v20
	v_exp_f32_e32 v168, v53
	v_lshlrev_b32_e32 v53, 16, v21
	v_exp_f32_e32 v158, v53
	v_lshlrev_b32_e32 v53, 16, v2
	v_exp_f32_e32 v154, v53
	v_lshlrev_b32_e32 v53, 16, v3
	v_exp_f32_e32 v144, v53
	v_lshlrev_b32_e32 v53, 16, v4
	v_exp_f32_e32 v138, v53
	v_lshlrev_b32_e32 v53, 16, v5
	v_exp_f32_e32 v112, v53
	v_add_lshl_u32 v53, s1, v240, 2
	v_exp_f32_e32 v172, v107
	v_lshlrev_b32_e32 v107, 16, v58
	ds_bpermute_b32 v114, v53, v69
	v_lshlrev_b32_e32 v53, 16, v34
	v_exp_f32_e32 v186, v107
	v_lshlrev_b32_e32 v107, 16, v59
	v_exp_f32_e32 v212, v53
	v_lshlrev_b32_e32 v53, 16, v35
; __device__ __forceinline__ float bflo(unsigned w) { return __uint_as_float(w << 16); }
; __device__ __forceinline__ float bfhi(unsigned w) { return __uint_as_float(w & 0xffff0000u); }
; __device__ __forceinline__ void lane_scan8(const u32x4 p0, const u32x4 p1, int d, float (&hl)[8], float (&pl)[8]) {
;     const float lv[8] = {bflo(p0.x), bflo(p0.y), bflo(p0.z), bflo(p0.w), bflo(p1.x), bflo(p1.y), bflo(p1.z), bflo(p1.w)};
;     const float uv[8] = {bfhi(p0.x), bfhi(p0.y), bfhi(p0.z), bfhi(p0.w), bfhi(p1.x), bfhi(p1.y), bfhi(p1.z), bfhi(p1.w)};
;     float H = 0.f, P = 1.f;
;     if (d == 0) {
; #pragma unroll
;         for (int k = 0; k < 8; ++k) { const float av = __builtin_amdgcn_exp2f(lv[k]); H = av * H + uv[k]; P *= av; hl[k] = H; pl[k] = P; }
;     } else {
; #pragma unroll
;         for (int k = 7; k >= 0; --k) { const float av = __builtin_amdgcn_exp2f(lv[k]); H = av * H + uv[k]; P *= av; hl[k] = H; pl[k] = P; }
;     }
; __device__ __forceinline__ void scan_final(const Args& a, int gw, int ngw, int lane, int layer) {
;     ...
;                     float hl[8], pl[8]; lane_scan8(lw[d][e], uw[d][e], d, hl, pl);
;                     float Pi = d == 0 ? pl[7] : pl[0], Hi = d == 0 ? hl[7] : hl[0];
; #pragma unroll
;                     for (int sft = 1; sft < 16; sft <<= 1) {
;                         const float Pp = d == 0 ? __shfl_up(Pi, sft, 16) : __shfl_down(Pi, sft, 16), Hp = d == 0 ? __shfl_up(Hi, sft, 16) : __shfl_down(Hi, sft, 16);
;                         const bool has = d == 0 ? (j >= sft) : (j + sft <= 15);
;                         if (has) { Hi = Pi * Hp + Hi; Pi = Pi * Pp; }
;                     }
;                     float Pe = d == 0 ? __shfl_up(Pi, 1, 16) : __shfl_down(Pi, 1, 16), He = d == 0 ? __shfl_up(Hi, 1, 16) : __shfl_down(Hi, 1, 16);
;                     if (d == 0 ? (j == 0) : (j == 15)) { Pe = 1.f; He = 0.f; }
	v_exp_f32_e32 v166, v107
	v_lshlrev_b32_e32 v107, 16, v61
	v_exp_f32_e32 v214, v53
	v_lshlrev_b32_e32 v53, 16, v36
	v_exp_f32_e32 v126, v107
	v_lshlrev_b32_e32 v107, 16, v60
	v_exp_f32_e32 v216, v53
	v_lshlrev_b32_e32 v53, 16, v37
	v_add_lshl_u32 v37, s1, v244, 2
	v_exp_f32_e32 v164, v107
	ds_bpermute_b32 v222, v37, v69
	v_lshlrev_b32_e32 v37, 16, v22
	v_exp_f32_e32 v109, v37
	v_lshlrev_b32_e32 v37, 16, v23
	v_exp_f32_e32 v189, v37
	v_lshlrev_b32_e32 v37, 16, v24
	v_exp_f32_e32 v210, v53
	v_lshlrev_b32_e32 v53, 16, v42
	v_exp_f32_e32 v169, v37
	v_lshlrev_b32_e32 v37, 16, v25
	v_pk_fma_f32 v[150:151], v[126:127], 0, v[150:151] op_sel_hi:[1,0,1]
	v_and_b32_e32 v61, 0xffff0000, v64
	v_and_b32_e32 v60, 0xffff0000, v60
	v_exp_f32_e32 v196, v53
	v_lshlrev_b32_e32 v53, 16, v43
	v_exp_f32_e32 v159, v37
	v_lshlrev_b32_e32 v37, 16, v6
	v_pk_fma_f32 v[60:61], v[164:165], v[150:151], v[60:61]
	v_and_b32_e32 v59, 0xffff0000, v62
	v_pk_mul_f32 v[62:63], v[126:127], v[164:165]
	v_exp_f32_e32 v218, v53
	v_lshlrev_b32_e32 v53, 16, v45
	v_exp_f32_e32 v155, v37
	v_lshlrev_b32_e32 v37, 16, v7
	v_and_b32_e32 v58, 0xffff0000, v58
	v_pk_mul_f32 v[164:165], v[166:167], v[62:63]
	v_pk_fma_f32 v[166:167], v[166:167], v[60:61], v[180:181]
	v_exp_f32_e32 v118, v53
	v_lshlrev_b32_e32 v53, 16, v44
	v_exp_f32_e32 v145, v37
	v_lshlrev_b32_e32 v37, 16, v8
	v_pk_mul_f32 v[184:185], v[186:187], v[164:165]
	v_pk_fma_f32 v[186:187], v[186:187], v[166:167], v[58:59]
	v_exp_f32_e32 v194, v53
	v_exp_f32_e32 v139, v37
	v_lshlrev_b32_e32 v37, 16, v9
	v_pk_mul_f32 v[198:199], v[172:173], v[184:185]
	v_pk_fma_f32 v[200:201], v[172:173], v[186:187], v[190:191]
	v_and_b32_e32 v53, 0xffff0000, v56
	v_and_b32_e32 v52, 0xffff0000, v52
	v_exp_f32_e32 v113, v37
	v_add_lshl_u32 v37, s1, v241, 2
	v_pk_mul_f32 v[64:65], v[170:171], v[198:199]
	v_pk_fma_f32 v[202:203], v[170:171], v[200:201], v[52:53]
	v_and_b32_e32 v53, 0xffff0000, v55
	v_and_b32_e32 v52, 0xffff0000, v51
	ds_bpermute_b32 v115, v37, v69
	v_lshlrev_b32_e32 v37, 16, v38
	v_pk_mul_f32 v[204:205], v[162:163], v[64:65]
	v_pk_fma_f32 v[206:207], v[162:163], v[202:203], v[52:53]
	v_and_b32_e32 v51, 0xffff0000, v54
	v_and_b32_e32 v50, 0xffff0000, v50
	v_exp_f32_e32 v213, v37
	v_lshlrev_b32_e32 v37, 16, v39
	v_pk_mul_f32 v[208:209], v[160:161], v[204:205]
	v_pk_fma_f32 v[50:51], v[160:161], v[206:207], v[50:51]
	v_exp_f32_e32 v215, v37
	v_lshlrev_b32_e32 v37, 16, v40
	v_and_b32_e32 v148, 0xffff0000, v26
	s_nop 1
	v_mov_b32_dpp v26, v208 row_shl:1 row_mask:0xf bank_mask:0xf bound_ctrl:1
	v_mov_b32_dpp v30, v50 row_shl:1 row_mask:0xf bank_mask:0xf bound_ctrl:1
	v_exp_f32_e32 v217, v37
	v_lshlrev_b32_e32 v37, 16, v41
	v_exp_f32_e32 v211, v37
	v_lshlrev_b32_e32 v37, 16, v46
	v_exp_f32_e32 v197, v37
	v_lshlrev_b32_e32 v37, 16, v47
	v_exp_f32_e32 v219, v37
	v_lshlrev_b32_e32 v37, 16, v49
	v_exp_f32_e32 v119, v37
	v_lshlrev_b32_e32 v37, 16, v48
	s_waitcnt lgkmcnt(0)
	v_fma_f32 v30, v208, v30, v50
	v_mul_f32_e32 v26, v208, v26
	v_exp_f32_e32 v195, v37
	v_add_lshl_u32 v37, s1, v237, 2
	v_cndmask_b32_e32 v30, v30, v50, vcc
	v_cndmask_b32_e32 v26, v26, v208, vcc
	ds_bpermute_b32 v223, v37, v69
	s_nop 1
	v_mov_b32_dpp v37, v26 row_shl:2 row_mask:0xf bank_mask:0xf bound_ctrl:1
	v_mov_b32_dpp v41, v30 row_shl:2 row_mask:0xf bank_mask:0xf bound_ctrl:1
	v_and_b32_e32 v44, 0xffff0000, v44
	v_pk_mul_f32 v[162:163], v[118:119], v[194:195]
	v_and_b32_e32 v36, 0xffff0000, v36
	s_waitcnt lgkmcnt(0)
	v_mul_f32_e32 v37, v26, v37
	s_waitcnt lgkmcnt(0)
	v_fma_f32 v41, v26, v41, v30
	v_cndmask_b32_e64 v30, v30, v41, s[46:47]
	v_cndmask_b32_e64 v26, v26, v37, s[46:47]
	s_nop 1
	v_mov_b32_dpp v37, v26 row_shl:4 row_mask:0xf bank_mask:0xf bound_ctrl:1
	v_mov_b32_dpp v41, v30 row_shl:4 row_mask:0xf bank_mask:0xf bound_ctrl:1
	v_pk_mul_f32 v[170:171], v[218:219], v[162:163]
	v_and_b32_e32 v34, 0xffff0000, v34
	v_pk_fma_f32 v[148:149], v[110:111], 0, v[148:149] op_sel_hi:[1,0,1]
	s_waitcnt lgkmcnt(0)
	v_mul_f32_e32 v37, v26, v37
	s_waitcnt lgkmcnt(0)
	v_fma_f32 v41, v26, v41, v30
	v_cndmask_b32_e64 v30, v30, v41, s[48:49]
	v_cndmask_b32_e64 v26, v26, v37, s[48:49]
	s_nop 1
	v_mov_b32_dpp v37, v26 row_shl:8 row_mask:0xf bank_mask:0xf bound_ctrl:1
	v_mov_b32_dpp v41, v30 row_shl:8 row_mask:0xf bank_mask:0xf bound_ctrl:1
	v_and_b32_e32 v31, 0xffff0000, v31
	v_and_b32_e32 v33, 0xffff0000, v33
	v_and_b32_e32 v15, 0xffff0000, v15
	s_waitcnt lgkmcnt(0)
	v_mul_f32_e32 v37, v26, v37
	s_waitcnt lgkmcnt(0)
	v_fma_f32 v41, v26, v41, v30
	v_cndmask_b32_e64 v30, v30, v41, s[50:51]
	v_cndmask_b32_e64 v26, v26, v37, s[50:51]
	s_nop 1
	v_mov_b32_dpp v37, v209 row_shl:1 row_mask:0xf bank_mask:0xf bound_ctrl:1
	v_mov_b32_dpp v41, v51 row_shl:1 row_mask:0xf bank_mask:0xf bound_ctrl:1
	v_mov_b32_dpp v26, v26 row_shl:1 row_mask:0xf bank_mask:0xf
	v_mov_b32_dpp v30, v30 row_shl:1 row_mask:0xf bank_mask:0xf
	v_and_b32_e32 v17, 0xffff0000, v17
	s_waitcnt lgkmcnt(0)
	v_mul_f32_e32 v37, v209, v37
	s_waitcnt lgkmcnt(0)
	v_fma_f32 v41, v209, v41, v51
	v_cndmask_b32_e32 v41, v41, v51, vcc
	v_cndmask_b32_e32 v37, v37, v209, vcc
	s_nop 1
	v_mov_b32_dpp v52, v37 row_shl:2 row_mask:0xf bank_mask:0xf bound_ctrl:1
	v_mov_b32_dpp v53, v41 row_shl:2 row_mask:0xf bank_mask:0xf bound_ctrl:1
	s_waitcnt lgkmcnt(0)
	v_cndmask_b32_e64 v54, v30, 0, vcc
	v_lshl_add_u64 v[106:107], s[62:63], 0, v[174:175]
	s_waitcnt lgkmcnt(0)
	v_mul_f32_e32 v52, v37, v52
	s_waitcnt lgkmcnt(0)
	v_fma_f32 v53, v37, v53, v41
	v_cndmask_b32_e64 v41, v41, v53, s[46:47]
	v_cndmask_b32_e64 v37, v37, v52, s[46:47]
	s_nop 1
	v_mov_b32_dpp v52, v37 row_shl:4 row_mask:0xf bank_mask:0xf bound_ctrl:1
	v_mov_b32_dpp v53, v41 row_shl:4 row_mask:0xf bank_mask:0xf bound_ctrl:1
	s_waitcnt lgkmcnt(0)
; __device__ __forceinline__ float bflo(unsigned w) { return __uint_as_float(w << 16); }
; __device__ __forceinline__ float bfhi(unsigned w) { return __uint_as_float(w & 0xffff0000u); }
; __device__ __forceinline__ float gelu_tanh(float x) { const float y = 0.7978845608028654f * (x + 0.044715f * x * x * x); const float e = __expf(2.0f * y); const float th = 1.0f - 2.0f * __builtin_amdgcn_rcpf(e + 1.0f); return 0.5f * x * (1.0f + th); }
; __device__ __forceinline__ void scan_final(const Args& a, int gw, int ngw, int lane, int layer) {
;     ...
;                     for (int sft = 1; sft < 16; sft <<= 1) {
;                         const float Pp = d == 0 ? __shfl_up(Pi, sft, 16) : __shfl_down(Pi, sft, 16), Hp = d == 0 ? __shfl_up(Hi, sft, 16) : __shfl_down(Hi, sft, 16);
;                         const bool has = d == 0 ? (j >= sft) : (j + sft <= 15);
;                         if (has) { Hi = Pi * Hp + Hi; Pi = Pi * Pp; }
;                     }
;                     float Pe = d == 0 ? __shfl_up(Pi, 1, 16) : __shfl_down(Pi, 1, 16), He = d == 0 ? __shfl_up(Hi, 1, 16) : __shfl_down(Hi, 1, 16);
;                     if (d == 0 ? (j == 0) : (j == 15)) { Pe = 1.f; He = 0.f; }
;                     const float c0 = __shfl(cv, eh * 4 + e + 8 * d, 16);
;                     const float sj = Pe * c0 + He;
;     ...
;             for (int k = 0; k < 8; ++k) { const float r0 = bflo(rgw[k].x), r1 = bfhi(rgw[k].x), r2 = bflo(rgw[k].y), r3 = bfhi(rgw[k].y);
;                 u32x2 w; w.x = pk2(acc[k][0] * gelu_tanh(r0), acc[k][1] * gelu_tanh(r1)); w.y = pk2(acc[k][2] * gelu_tanh(r2), acc[k][3] * gelu_tanh(r3));
	v_mul_f32_e32 v52, v37, v52
	s_waitcnt lgkmcnt(0)
	v_fma_f32 v53, v37, v53, v41
	v_cndmask_b32_e64 v41, v41, v53, s[48:49]
	v_cndmask_b32_e64 v37, v37, v52, s[48:49]
	s_nop 1
	v_mov_b32_dpp v52, v37 row_shl:8 row_mask:0xf bank_mask:0xf bound_ctrl:1
	v_mov_b32_dpp v53, v41 row_shl:8 row_mask:0xf bank_mask:0xf bound_ctrl:1
	s_waitcnt lgkmcnt(0)
	v_mul_f32_e32 v52, v37, v52
	s_waitcnt lgkmcnt(0)
	v_fma_f32 v53, v37, v53, v41
	v_cndmask_b32_e64 v41, v41, v53, s[50:51]
	v_cndmask_b32_e64 v37, v37, v52, s[50:51]
	s_nop 1
	v_mov_b32_dpp v37, v37 row_shl:1 row_mask:0xf bank_mask:0xf
	v_mov_b32_dpp v41, v41 row_shl:1 row_mask:0xf bank_mask:0xf
	v_cndmask_b32_e64 v52, v26, 1.0, vcc
	s_waitcnt lgkmcnt(0)
	v_cndmask_b32_e64 v53, v37, 1.0, vcc
	s_waitcnt lgkmcnt(0)
	v_cndmask_b32_e64 v55, v41, 0, vcc
	v_pk_fma_f32 v[58:59], v[52:53], v[192:193], v[54:55]
	v_and_b32_e32 v37, 0xffff0000, v40
	v_pk_fma_f32 v[54:55], v[208:209], v[58:59], v[50:51]
	v_lshlrev_b32_e32 v50, 16, v182
	v_mul_f32_e32 v26, 0x3d372713, v50
	v_mul_f32_e32 v26, v26, v50
	v_mov_b32_e32 v30, v50
	v_fmac_f32_e32 v30, v26, v30
	v_mul_f32_e32 v26, 0x3f4c422a, v30
	v_add_f32_e32 v26, v26, v26
	v_mul_f32_e32 v26, 0x3fb8aa3b, v26
	v_exp_f32_e32 v26, v26
	v_and_b32_e32 v51, 0xffff0000, v182
	v_mov_b32_e32 v30, v51
	v_add_f32_e32 v26, 1.0, v26
	v_rcp_f32_e32 v52, v26
	v_mul_f32_e32 v26, 0x3d372713, v51
	v_mul_f32_e32 v26, v26, v51
	v_fmac_f32_e32 v30, v26, v30
	v_mul_f32_e32 v26, 0x3f4c422a, v30
	v_add_f32_e32 v26, v26, v26
	v_mul_f32_e32 v26, 0x3fb8aa3b, v26
	v_exp_f32_e32 v26, v26
	v_pk_mul_f32 v[50:51], v[50:51], 0.5 op_sel_hi:[1,0]
	v_add_f32_e32 v26, 1.0, v26
	v_rcp_f32_e32 v53, v26
	s_nop 0
	v_pk_fma_f32 v[52:53], v[52:53], 2.0, 1.0 op_sel_hi:[1,0,0] neg_lo:[1,0,0] neg_hi:[1,0,0]
	s_nop 0
	v_pk_add_f32 v[52:53], v[52:53], 1.0 op_sel_hi:[1,0]
	s_nop 0
	v_pk_mul_f32 v[56:57], v[50:51], v[52:53]
	v_and_b32_e32 v53, 0xffff0000, v49
	v_and_b32_e32 v52, 0xffff0000, v45
	v_pk_fma_f32 v[52:53], v[118:119], 0, v[52:53] op_sel_hi:[1,0,1]
	v_and_b32_e32 v45, 0xffff0000, v48
	v_pk_fma_f32 v[160:161], v[194:195], v[52:53], v[44:45]
	v_and_b32_e32 v49, 0xffff0000, v47
	v_and_b32_e32 v48, 0xffff0000, v43
	v_and_b32_e32 v47, 0xffff0000, v46
	v_and_b32_e32 v46, 0xffff0000, v42
	v_pk_fma_f32 v[172:173], v[218:219], v[160:161], v[48:49]
	v_pk_mul_f32 v[194:195], v[196:197], v[170:171]
	v_pk_fma_f32 v[196:197], v[196:197], v[172:173], v[46:47]
	v_pk_mul_f32 v[208:209], v[210:211], v[194:195]
	v_pk_fma_f32 v[210:211], v[210:211], v[196:197], v[220:221]
	v_pk_mul_f32 v[44:45], v[216:217], v[208:209]
	v_pk_fma_f32 v[46:47], v[216:217], v[210:211], v[36:37]
	v_and_b32_e32 v37, 0xffff0000, v39
	v_and_b32_e32 v36, 0xffff0000, v35
	v_pk_mul_f32 v[42:43], v[214:215], v[44:45]
	v_pk_fma_f32 v[48:49], v[214:215], v[46:47], v[36:37]
	v_and_b32_e32 v35, 0xffff0000, v38
	v_pk_mul_f32 v[180:181], v[212:213], v[42:43]
	v_pk_fma_f32 v[34:35], v[212:213], v[48:49], v[34:35]
	v_and_b32_e32 v51, 0xffff0000, v22
	v_and_b32_e32 v50, 0xffff0000, v18
	s_nop 1
	v_mov_b32_dpp v18, v180 row_shl:1 row_mask:0xf bank_mask:0xf bound_ctrl:1
	v_mov_b32_dpp v22, v34 row_shl:1 row_mask:0xf bank_mask:0xf bound_ctrl:1
	v_pk_fma_f32 v[50:51], v[108:109], 0, v[50:51] op_sel_hi:[1,0,1]
	s_waitcnt lgkmcnt(0)
	v_mul_f32_e32 v18, v180, v18
	s_waitcnt lgkmcnt(0)
	v_fma_f32 v22, v180, v22, v34
	v_cndmask_b32_e32 v22, v22, v34, vcc
	v_cndmask_b32_e32 v18, v18, v180, vcc
	s_nop 1
	v_mov_b32_dpp v26, v18 row_shl:2 row_mask:0xf bank_mask:0xf bound_ctrl:1
	v_mov_b32_dpp v30, v22 row_shl:2 row_mask:0xf bank_mask:0xf bound_ctrl:1
	s_waitcnt lgkmcnt(0)
	v_mul_f32_e32 v26, v18, v26
	s_waitcnt lgkmcnt(0)
	v_fma_f32 v30, v18, v30, v22
	v_cndmask_b32_e64 v22, v22, v30, s[46:47]
	v_cndmask_b32_e64 v18, v18, v26, s[46:47]
	s_nop 1
	v_mov_b32_dpp v26, v18 row_shl:4 row_mask:0xf bank_mask:0xf bound_ctrl:1
	v_mov_b32_dpp v30, v22 row_shl:4 row_mask:0xf bank_mask:0xf bound_ctrl:1
	s_waitcnt lgkmcnt(0)
	v_mul_f32_e32 v26, v18, v26
	s_waitcnt lgkmcnt(0)
	v_fma_f32 v30, v18, v30, v22
	v_cndmask_b32_e64 v22, v22, v30, s[48:49]
	v_cndmask_b32_e64 v18, v18, v26, s[48:49]
	s_nop 1
	v_mov_b32_dpp v26, v18 row_shl:8 row_mask:0xf bank_mask:0xf bound_ctrl:1
	v_mov_b32_dpp v30, v22 row_shl:8 row_mask:0xf bank_mask:0xf bound_ctrl:1
	s_waitcnt lgkmcnt(0)
	v_mul_f32_e32 v26, v18, v26
	s_waitcnt lgkmcnt(0)
	v_fma_f32 v30, v18, v30, v22
	v_cndmask_b32_e64 v22, v22, v30, s[50:51]
	v_cndmask_b32_e64 v18, v18, v26, s[50:51]
	s_nop 1
	v_mov_b32_dpp v26, v181 row_shl:1 row_mask:0xf bank_mask:0xf bound_ctrl:1
	v_mov_b32_dpp v30, v35 row_shl:1 row_mask:0xf bank_mask:0xf bound_ctrl:1
	v_mov_b32_dpp v18, v18 row_shl:1 row_mask:0xf bank_mask:0xf
	v_mov_b32_dpp v22, v22 row_shl:1 row_mask:0xf bank_mask:0xf
	s_waitcnt lgkmcnt(0)
	v_mul_f32_e32 v26, v181, v26
	s_waitcnt lgkmcnt(0)
	v_fma_f32 v30, v181, v30, v35
	v_cndmask_b32_e32 v30, v30, v35, vcc
	v_cndmask_b32_e32 v26, v26, v181, vcc
	s_nop 1
	v_mov_b32_dpp v36, v26 row_shl:2 row_mask:0xf bank_mask:0xf bound_ctrl:1
	v_mov_b32_dpp v37, v30 row_shl:2 row_mask:0xf bank_mask:0xf bound_ctrl:1
	s_waitcnt lgkmcnt(0)
	v_cndmask_b32_e64 v38, v22, 0, vcc
	s_waitcnt lgkmcnt(0)
	v_mul_f32_e32 v36, v26, v36
	s_waitcnt lgkmcnt(0)
	v_fma_f32 v37, v26, v37, v30
	v_cndmask_b32_e64 v30, v30, v37, s[46:47]
	v_cndmask_b32_e64 v26, v26, v36, s[46:47]
	s_nop 1
	v_mov_b32_dpp v36, v26 row_shl:4 row_mask:0xf bank_mask:0xf bound_ctrl:1
	v_mov_b32_dpp v37, v30 row_shl:4 row_mask:0xf bank_mask:0xf bound_ctrl:1
	s_waitcnt lgkmcnt(0)
	v_mul_f32_e32 v36, v26, v36
	s_waitcnt lgkmcnt(0)
; __device__ __forceinline__ float bflo(unsigned w) { return __uint_as_float(w << 16); }
; __device__ __forceinline__ float bfhi(unsigned w) { return __uint_as_float(w & 0xffff0000u); }
; __device__ __forceinline__ float gelu_tanh(float x) { const float y = 0.7978845608028654f * (x + 0.044715f * x * x * x); const float e = __expf(2.0f * y); const float th = 1.0f - 2.0f * __builtin_amdgcn_rcpf(e + 1.0f); return 0.5f * x * (1.0f + th); }
; __device__ __forceinline__ void scan_final(const Args& a, int gw, int ngw, int lane, int layer) {
;     ...
;                     for (int sft = 1; sft < 16; sft <<= 1) {
;                         const float Pp = d == 0 ? __shfl_up(Pi, sft, 16) : __shfl_down(Pi, sft, 16), Hp = d == 0 ? __shfl_up(Hi, sft, 16) : __shfl_down(Hi, sft, 16);
;                         const bool has = d == 0 ? (j >= sft) : (j + sft <= 15);
;                         if (has) { Hi = Pi * Hp + Hi; Pi = Pi * Pp; }
;                     }
;                     float Pe = d == 0 ? __shfl_up(Pi, 1, 16) : __shfl_down(Pi, 1, 16), He = d == 0 ? __shfl_up(Hi, 1, 16) : __shfl_down(Hi, 1, 16);
;                     if (d == 0 ? (j == 0) : (j == 15)) { Pe = 1.f; He = 0.f; }
;                     const float c0 = __shfl(cv, eh * 4 + e + 8 * d, 16);
;                     const float sj = Pe * c0 + He;
;     ...
;             for (int k = 0; k < 8; ++k) { const float r0 = bflo(rgw[k].x), r1 = bfhi(rgw[k].x), r2 = bflo(rgw[k].y), r3 = bfhi(rgw[k].y);
;                 u32x2 w; w.x = pk2(acc[k][0] * gelu_tanh(r0), acc[k][1] * gelu_tanh(r1)); w.y = pk2(acc[k][2] * gelu_tanh(r2), acc[k][3] * gelu_tanh(r3));
	v_fma_f32 v37, v26, v37, v30
	v_cndmask_b32_e64 v30, v30, v37, s[48:49]
	v_cndmask_b32_e64 v26, v26, v36, s[48:49]
	s_nop 1
	v_mov_b32_dpp v36, v26 row_shl:8 row_mask:0xf bank_mask:0xf bound_ctrl:1
	v_mov_b32_dpp v37, v30 row_shl:8 row_mask:0xf bank_mask:0xf bound_ctrl:1
	s_waitcnt lgkmcnt(0)
	v_mul_f32_e32 v36, v26, v36
	s_waitcnt lgkmcnt(0)
	v_fma_f32 v37, v26, v37, v30
	v_cndmask_b32_e64 v30, v30, v37, s[50:51]
	v_cndmask_b32_e64 v26, v26, v36, s[50:51]
	s_nop 1
	v_mov_b32_dpp v26, v26 row_shl:1 row_mask:0xf bank_mask:0xf
	v_mov_b32_dpp v30, v30 row_shl:1 row_mask:0xf bank_mask:0xf
	v_cndmask_b32_e64 v36, v18, 1.0, vcc
	s_waitcnt lgkmcnt(0)
	v_cndmask_b32_e64 v37, v26, 1.0, vcc
	s_waitcnt lgkmcnt(0)
	v_cndmask_b32_e64 v39, v30, 0, vcc
	v_pk_fma_f32 v[40:41], v[36:37], v[222:223], v[38:39]
	v_lshlrev_b32_e32 v36, 16, v183
	v_mul_f32_e32 v18, 0x3d372713, v36
	v_mul_f32_e32 v18, v18, v36
	v_mov_b32_e32 v22, v36
	v_fmac_f32_e32 v22, v18, v22
	v_mul_f32_e32 v18, 0x3f4c422a, v22
	v_add_f32_e32 v18, v18, v18
	v_mul_f32_e32 v18, 0x3fb8aa3b, v18
	v_exp_f32_e32 v18, v18
	v_and_b32_e32 v37, 0xffff0000, v183
	v_mov_b32_e32 v22, v37
	v_lshlrev_b32_e32 v26, 16, v152
	v_add_f32_e32 v18, 1.0, v18
	v_rcp_f32_e32 v38, v18
	v_mul_f32_e32 v18, 0x3d372713, v37
	v_mul_f32_e32 v18, v18, v37
	v_fmac_f32_e32 v22, v18, v22
	v_mul_f32_e32 v18, 0x3f4c422a, v22
	v_add_f32_e32 v18, v18, v18
	v_mul_f32_e32 v18, 0x3fb8aa3b, v18
	v_exp_f32_e32 v18, v18
	v_mov_b32_e32 v22, v26
	v_and_b32_e32 v30, 0xffff0000, v27
	v_and_b32_e32 v27, 0xffff0000, v152
	v_add_f32_e32 v18, 1.0, v18
	v_rcp_f32_e32 v39, v18
	v_mul_f32_e32 v18, 0x3d372713, v26
	v_mul_f32_e32 v18, v18, v26
	v_fmac_f32_e32 v22, v18, v22
	v_mul_f32_e32 v18, 0x3f4c422a, v22
	v_add_f32_e32 v18, v18, v18
	v_mul_f32_e32 v18, 0x3fb8aa3b, v18
	v_exp_f32_e32 v18, v18
	v_pk_fma_f32 v[190:191], v[156:157], v[148:149], v[30:31]
	v_mov_b32_e32 v22, v27
	v_pk_mul_f32 v[182:183], v[110:111], v[156:157]
	v_add_f32_e32 v18, 1.0, v18
	v_rcp_f32_e32 v30, v18
	v_mul_f32_e32 v18, 0x3d372713, v27
	v_mul_f32_e32 v18, v18, v27
	v_fmac_f32_e32 v22, v18, v22
	v_mul_f32_e32 v18, 0x3f4c422a, v22
	v_add_f32_e32 v18, v18, v18
	v_mul_f32_e32 v18, 0x3fb8aa3b, v18
	v_exp_f32_e32 v18, v18
	v_pk_mul_f32 v[26:27], v[26:27], 0.5 op_sel_hi:[1,0]
	v_pk_fma_f32 v[156:157], v[204:205], v[58:59], v[206:207]
	v_pk_fma_f32 v[44:45], v[44:45], v[40:41], v[46:47]
	v_add_f32_e32 v18, 1.0, v18
	v_rcp_f32_e32 v31, v18
	v_pk_fma_f32 v[34:35], v[180:181], v[40:41], v[34:35]
	v_pk_fma_f32 v[38:39], v[38:39], 2.0, 1.0 op_sel_hi:[1,0,0] neg_lo:[1,0,0] neg_hi:[1,0,0]
	v_pk_mul_f32 v[36:37], v[36:37], 0.5 op_sel_hi:[1,0]
	v_pk_fma_f32 v[30:31], v[30:31], 2.0, 1.0 op_sel_hi:[1,0,0] neg_lo:[1,0,0] neg_hi:[1,0,0]
	v_pk_add_f32 v[38:39], v[38:39], 1.0 op_sel_hi:[1,0]
	v_pk_add_f32 v[30:31], v[30:31], 1.0 op_sel_hi:[1,0]
	v_pk_mul_f32 v[38:39], v[36:37], v[38:39]
	v_pk_mul_f32 v[192:193], v[26:27], v[30:31]
	v_lshlrev_b32_e32 v30, 16, v153
	v_and_b32_e32 v26, 0xffff0000, v19
	v_pk_fma_f32 v[18:19], v[42:43], v[40:41], v[48:49]
	v_mul_f32_e32 v42, 0x3d372713, v30
	v_mul_f32_e32 v42, v42, v30
	v_mov_b32_e32 v43, v30
	v_and_b32_e32 v31, 0xffff0000, v153
	v_fmac_f32_e32 v43, v42, v43
	v_mul_f32_e32 v42, 0x3f4c422a, v43
	v_mul_f32_e32 v43, 0x3d372713, v31
	v_mul_f32_e32 v43, v43, v31
	v_mov_b32_e32 v48, v31
	v_fmac_f32_e32 v48, v43, v48
	v_mul_f32_e32 v43, 0x3f4c422a, v48
	v_and_b32_e32 v49, 0xffff0000, v32
	v_and_b32_e32 v48, 0xffff0000, v28
	v_pk_fma_f32 v[204:205], v[146:147], v[190:191], v[48:49]
	v_lshlrev_b32_e32 v48, 16, v142
	v_mul_f32_e32 v28, 0x3d372713, v48
	v_mul_f32_e32 v28, v28, v48
	v_mov_b32_e32 v32, v48
	v_fmac_f32_e32 v32, v28, v32
	v_mul_f32_e32 v28, 0x3f4c422a, v32
	v_add_f32_e32 v28, v28, v28
	v_mul_f32_e32 v28, 0x3fb8aa3b, v28
	v_exp_f32_e32 v28, v28
	v_and_b32_e32 v27, 0xffff0000, v23
	v_and_b32_e32 v49, 0xffff0000, v142
	v_pk_mul_f32 v[22:23], v[108:109], v[188:189]
	v_add_f32_e32 v28, 1.0, v28
	v_pk_fma_f32 v[26:27], v[188:189], v[50:51], v[26:27]
	v_pk_fma_f32 v[188:189], v[64:65], v[58:59], v[202:203]
	v_rcp_f32_e32 v64, v28
	v_mul_f32_e32 v28, 0x3d372713, v49
	v_mul_f32_e32 v28, v28, v49
	v_mov_b32_e32 v32, v49
	v_fmac_f32_e32 v32, v28, v32
	v_mul_f32_e32 v28, 0x3f4c422a, v32
	v_add_f32_e32 v28, v28, v28
	v_mul_f32_e32 v28, 0x3fb8aa3b, v28
	v_exp_f32_e32 v28, v28
	v_pk_mul_f32 v[48:49], v[48:49], 0.5 op_sel_hi:[1,0]
	v_and_b32_e32 v32, 0xffff0000, v29
	v_and_b32_e32 v29, 0xffff0000, v136
	v_add_f32_e32 v28, 1.0, v28
	v_rcp_f32_e32 v65, v28
	v_lshlrev_b32_e32 v28, 16, v136
	v_pk_mul_f32 v[46:47], v[168:169], v[22:23]
	v_pk_mul_f32 v[202:203], v[146:147], v[182:183]
	v_pk_fma_f32 v[64:65], v[64:65], 2.0, 1.0 op_sel_hi:[1,0,0] neg_lo:[1,0,0] neg_hi:[1,0,0]
	v_and_b32_e32 v146, 0xffff0000, v2
	v_pk_add_f32 v[64:65], v[64:65], 1.0 op_sel_hi:[1,0]
	v_and_b32_e32 v147, 0xffff0000, v6
	v_pk_mul_f32 v[206:207], v[48:49], v[64:65]
	v_lshlrev_b32_e32 v64, 16, v143
	v_and_b32_e32 v48, 0xffff0000, v20
	v_mul_f32_e32 v20, 0x3d372713, v64
	v_and_b32_e32 v49, 0xffff0000, v24
	v_mul_f32_e32 v20, v20, v64
	v_mov_b32_e32 v24, v64
	v_fmac_f32_e32 v24, v20, v24
	v_mul_f32_e32 v20, 0x3f4c422a, v24
	v_add_f32_e32 v20, v20, v20
	v_mul_f32_e32 v20, 0x3fb8aa3b, v20
	v_exp_f32_e32 v20, v20
	v_and_b32_e32 v65, 0xffff0000, v143
	v_mov_b32_e32 v24, v65
	v_pk_fma_f32 v[48:49], v[168:169], v[26:27], v[48:49]
	v_add_f32_e32 v20, 1.0, v20
	v_rcp_f32_e32 v142, v20
	v_mul_f32_e32 v20, 0x3d372713, v65
	v_mul_f32_e32 v20, v20, v65
	v_fmac_f32_e32 v24, v20, v24
	v_mul_f32_e32 v20, 0x3f4c422a, v24
	v_add_f32_e32 v20, v20, v20
	v_mul_f32_e32 v20, 0x3fb8aa3b, v20
	v_exp_f32_e32 v20, v20
; __device__ __forceinline__ float bflo(unsigned w) { return __uint_as_float(w << 16); }
; __device__ __forceinline__ float bfhi(unsigned w) { return __uint_as_float(w & 0xffff0000u); }
; __device__ __forceinline__ float gelu_tanh(float x) { const float y = 0.7978845608028654f * (x + 0.044715f * x * x * x); const float e = __expf(2.0f * y); const float th = 1.0f - 2.0f * __builtin_amdgcn_rcpf(e + 1.0f); return 0.5f * x * (1.0f + th); }
; __device__ __forceinline__ void scan_final(const Args& a, int gw, int ngw, int lane, int layer) {
;     ...
; #pragma unroll
;                     for (int k = 0; k < 8; ++k) { const float hv = hl[k] + pl[k] * sj; if (d == 0) acc[k][e] = hv; else acc[k][e] += hv; }
;     ...
;             for (int k = 0; k < 8; ++k) { const float r0 = bflo(rgw[k].x), r1 = bfhi(rgw[k].x), r2 = bflo(rgw[k].y), r3 = bfhi(rgw[k].y);
;                 u32x2 w; w.x = pk2(acc[k][0] * gelu_tanh(r0), acc[k][1] * gelu_tanh(r1)); w.y = pk2(acc[k][2] * gelu_tanh(r2), acc[k][3] * gelu_tanh(r3));
	v_mov_b32_e32 v24, v28
	v_pk_fma_f32 v[168:169], v[198:199], v[58:59], v[200:201]
	v_pk_fma_f32 v[200:201], v[140:141], v[204:205], v[32:33]
	v_add_f32_e32 v20, 1.0, v20
	v_rcp_f32_e32 v143, v20
	v_mul_f32_e32 v20, 0x3d372713, v28
	v_mul_f32_e32 v20, v20, v28
	v_fmac_f32_e32 v24, v20, v24
	v_mul_f32_e32 v20, 0x3f4c422a, v24
	v_add_f32_e32 v20, v20, v20
	v_mul_f32_e32 v20, 0x3fb8aa3b, v20
	v_exp_f32_e32 v20, v20
	v_mov_b32_e32 v24, v29
	v_pk_mul_f32 v[198:199], v[140:141], v[202:203]
	v_and_b32_e32 v141, 0xffff0000, v14
	v_add_f32_e32 v20, 1.0, v20
	v_rcp_f32_e32 v32, v20
	v_mul_f32_e32 v20, 0x3d372713, v29
	v_mul_f32_e32 v20, v20, v29
	v_fmac_f32_e32 v24, v20, v24
	v_mul_f32_e32 v20, 0x3f4c422a, v24
	v_add_f32_e32 v20, v20, v20
	v_mul_f32_e32 v20, 0x3fb8aa3b, v20
	v_exp_f32_e32 v20, v20
	v_pk_mul_f32 v[28:29], v[28:29], 0.5 op_sel_hi:[1,0]
	v_add_f32_e32 v42, v42, v42
	v_add_f32_e32 v43, v43, v43
	v_add_f32_e32 v20, 1.0, v20
	v_rcp_f32_e32 v33, v20
	v_mul_f32_e32 v42, 0x3fb8aa3b, v42
	v_mul_f32_e32 v43, 0x3fb8aa3b, v43
	v_exp_f32_e32 v42, v42
	v_pk_fma_f32 v[32:33], v[32:33], 2.0, 1.0 op_sel_hi:[1,0,0] neg_lo:[1,0,0] neg_hi:[1,0,0]
	v_exp_f32_e32 v43, v43
	v_pk_add_f32 v[32:33], v[32:33], 1.0 op_sel_hi:[1,0]
	v_add_f32_e32 v42, 1.0, v42
	v_pk_mul_f32 v[212:213], v[28:29], v[32:33]
	v_lshlrev_b32_e32 v32, 16, v137
	v_mul_f32_e32 v136, 0x3d372713, v32
	v_and_b32_e32 v33, 0xffff0000, v137
	v_mul_f32_e32 v136, v136, v32
	v_mov_b32_e32 v137, v32
	v_fmac_f32_e32 v137, v136, v137
	v_mul_f32_e32 v136, 0x3f4c422a, v137
	v_mul_f32_e32 v137, 0x3d372713, v33
	v_mul_f32_e32 v137, v137, v33
	v_mov_b32_e32 v140, v33
	v_fmac_f32_e32 v140, v137, v140
	v_and_b32_e32 v29, 0xffff0000, v25
	v_and_b32_e32 v28, 0xffff0000, v21
	v_mul_f32_e32 v137, 0x3f4c422a, v140
	v_and_b32_e32 v140, 0xffff0000, v10
	v_pk_mul_f32 v[24:25], v[158:159], v[46:47]
	v_pk_fma_f32 v[28:29], v[158:159], v[48:49], v[28:29]
	v_pk_fma_f32 v[158:159], v[184:185], v[58:59], v[186:187]
	v_pk_mul_f32 v[184:185], v[134:135], v[198:199]
	v_pk_fma_f32 v[186:187], v[134:135], v[200:201], v[140:141]
	v_lshlrev_b32_e32 v134, 16, v132
	v_and_b32_e32 v135, 0xffff0000, v132
	v_mul_f32_e32 v10, 0x3d372713, v134
	v_lshlrev_b32_e32 v132, 16, v133
	v_mul_f32_e32 v10, v10, v134
	v_mov_b32_e32 v14, v134
	v_mul_f32_e32 v2, 0x3d372713, v132
	v_fmac_f32_e32 v14, v10, v14
	v_mul_f32_e32 v2, v2, v132
	v_mov_b32_e32 v6, v132
	v_mul_f32_e32 v10, 0x3f4c422a, v14
	v_fmac_f32_e32 v6, v2, v6
	v_add_f32_e32 v10, v10, v10
	v_mul_f32_e32 v2, 0x3f4c422a, v6
	v_mul_f32_e32 v10, 0x3fb8aa3b, v10
	v_add_f32_e32 v2, v2, v2
	v_exp_f32_e32 v10, v10
	v_mul_f32_e32 v2, 0x3fb8aa3b, v2
	v_exp_f32_e32 v2, v2
	v_and_b32_e32 v133, 0xffff0000, v133
	v_add_f32_e32 v10, 1.0, v10
	v_rcp_f32_e32 v140, v10
	v_mul_f32_e32 v10, 0x3d372713, v135
	v_add_f32_e32 v2, 1.0, v2
	v_mul_f32_e32 v10, v10, v135
	v_mov_b32_e32 v14, v135
	v_rcp_f32_e32 v152, v2
	v_mul_f32_e32 v2, 0x3d372713, v133
	v_fmac_f32_e32 v14, v10, v14
	v_mul_f32_e32 v2, v2, v133
	v_mov_b32_e32 v6, v133
	v_mul_f32_e32 v10, 0x3f4c422a, v14
	v_fmac_f32_e32 v6, v2, v6
	v_add_f32_e32 v10, v10, v10
	v_mul_f32_e32 v2, 0x3f4c422a, v6
	v_mul_f32_e32 v10, 0x3fb8aa3b, v10
	v_add_f32_e32 v2, v2, v2
	v_exp_f32_e32 v10, v10
	v_mul_f32_e32 v2, 0x3fb8aa3b, v2
	v_exp_f32_e32 v2, v2
	v_pk_mul_f32 v[134:135], v[134:135], 0.5 op_sel_hi:[1,0]
	v_add_f32_e32 v10, 1.0, v10
	v_rcp_f32_e32 v141, v10
	v_add_f32_e32 v2, 1.0, v2
	v_lshlrev_b32_e32 v10, 16, v128
	v_rcp_f32_e32 v153, v2
	v_mul_f32_e32 v2, 0x3d372713, v10
	v_mul_f32_e32 v2, v2, v10
	v_mov_b32_e32 v6, v10
	v_fmac_f32_e32 v6, v2, v6
	v_mul_f32_e32 v2, 0x3f4c422a, v6
	v_add_f32_e32 v2, v2, v2
	v_mul_f32_e32 v2, 0x3fb8aa3b, v2
	v_exp_f32_e32 v2, v2
	v_pk_fma_f32 v[140:141], v[140:141], 2.0, 1.0 op_sel_hi:[1,0,0] neg_lo:[1,0,0] neg_hi:[1,0,0]
	v_and_b32_e32 v14, 0xffff0000, v11
	v_pk_add_f32 v[140:141], v[140:141], 1.0 op_sel_hi:[1,0]
	v_and_b32_e32 v11, 0xffff0000, v128
	v_add_f32_e32 v2, 1.0, v2
	v_pk_fma_f32 v[20:21], v[208:209], v[40:41], v[210:211]
	v_pk_mul_f32 v[208:209], v[134:135], v[140:141]
	v_pk_mul_f32 v[140:141], v[154:155], v[24:25]
	v_pk_fma_f32 v[146:147], v[154:155], v[28:29], v[146:147]
	v_pk_fma_f32 v[154:155], v[164:165], v[58:59], v[166:167]
	v_pk_fma_f32 v[166:167], v[130:131], v[186:187], v[14:15]
	v_rcp_f32_e32 v14, v2
	v_mul_f32_e32 v2, 0x3d372713, v11
	v_mul_f32_e32 v2, v2, v11
	v_mov_b32_e32 v6, v11
	v_fmac_f32_e32 v6, v2, v6
	v_mul_f32_e32 v2, 0x3f4c422a, v6
	v_add_f32_e32 v2, v2, v2
	v_mul_f32_e32 v2, 0x3fb8aa3b, v2
	v_exp_f32_e32 v2, v2
	v_pk_mul_f32 v[10:11], v[10:11], 0.5 op_sel_hi:[1,0]
	v_pk_fma_f32 v[134:135], v[194:195], v[40:41], v[196:197]
	v_pk_mul_f32 v[164:165], v[130:131], v[184:185]
	v_add_f32_e32 v2, 1.0, v2
	v_rcp_f32_e32 v15, v2
	v_lshlrev_b32_e32 v2, 16, v129
	v_add_f32_e32 v136, v136, v136
	v_add_f32_e32 v137, v137, v137
	v_pk_fma_f32 v[14:15], v[14:15], 2.0, 1.0 op_sel_hi:[1,0,0] neg_lo:[1,0,0] neg_hi:[1,0,0]
	v_mul_f32_e32 v136, 0x3fb8aa3b, v136
	v_pk_add_f32 v[14:15], v[14:15], 1.0 op_sel_hi:[1,0]
	v_mul_f32_e32 v137, 0x3fb8aa3b, v137
	v_pk_mul_f32 v[194:195], v[10:11], v[14:15]
	v_and_b32_e32 v15, 0xffff0000, v7
	v_and_b32_e32 v14, 0xffff0000, v3
	v_pk_fma_f32 v[130:131], v[144:145], v[146:147], v[14:15]
	v_mul_f32_e32 v14, 0x3d372713, v2
	v_mul_f32_e32 v14, v14, v2
	v_mov_b32_e32 v15, v2
	v_and_b32_e32 v3, 0xffff0000, v129
	v_fmac_f32_e32 v15, v14, v15
	v_mul_f32_e32 v14, 0x3f4c422a, v15
	v_mul_f32_e32 v15, 0x3d372713, v3
	v_mul_f32_e32 v15, v15, v3
	v_mov_b32_e32 v128, v3
	v_fmac_f32_e32 v128, v15, v128
	v_mul_f32_e32 v15, 0x3f4c422a, v128
	v_add_f32_e32 v14, v14, v14
	v_add_f32_e32 v15, v15, v15
; __device__ __forceinline__ void scan_final(const Args& a, int gw, int ngw, int lane, int layer) {
;     ...
;                     float hl[8], pl[8]; lane_scan8(lw[d][e], uw[d][e], d, hl, pl);
;                     float Pi = d == 0 ? pl[7] : pl[0], Hi = d == 0 ? hl[7] : hl[0];
; #pragma unroll
;                     for (int sft = 1; sft < 16; sft <<= 1) {
;                         const float Pp = d == 0 ? __shfl_up(Pi, sft, 16) : __shfl_down(Pi, sft, 16), Hp = d == 0 ? __shfl_up(Hi, sft, 16) : __shfl_down(Hi, sft, 16);
;                         const bool has = d == 0 ? (j >= sft) : (j + sft <= 15);
;                         if (has) { Hi = Pi * Hp + Hi; Pi = Pi * Pp; }
;                     }
;                     float Pe = d == 0 ? __shfl_up(Pi, 1, 16) : __shfl_down(Pi, 1, 16), He = d == 0 ? __shfl_up(Hi, 1, 16) : __shfl_down(Hi, 1, 16);
;                     if (d == 0 ? (j == 0) : (j == 15)) { Pe = 1.f; He = 0.f; }
	v_mul_f32_e32 v14, 0x3fb8aa3b, v14
	v_mul_f32_e32 v15, 0x3fb8aa3b, v15
	v_exp_f32_e32 v14, v14
	v_exp_f32_e32 v15, v15
	v_pk_mul_f32 v[2:3], v[2:3], 0.5 op_sel_hi:[1,0]
	v_pk_mul_f32 v[10:11], v[144:145], v[140:141]
	v_add_f32_e32 v14, 1.0, v14
	v_add_f32_e32 v15, 1.0, v15
	v_rcp_f32_e32 v14, v14
	v_rcp_f32_e32 v15, v15
	v_and_b32_e32 v144, 0xffff0000, v12
	v_and_b32_e32 v145, 0xffff0000, v16
	v_pk_fma_f32 v[6:7], v[170:171], v[40:41], v[172:173]
	v_pk_fma_f32 v[14:15], v[14:15], 2.0, 1.0 op_sel_hi:[1,0,0] neg_lo:[1,0,0] neg_hi:[1,0,0]
	v_pk_mul_f32 v[170:171], v[122:123], v[164:165]
	v_pk_add_f32 v[14:15], v[14:15], 1.0 op_sel_hi:[1,0]
	v_pk_fma_f32 v[144:145], v[122:123], v[166:167], v[144:145]
	v_pk_mul_f32 v[128:129], v[2:3], v[14:15]
	v_pk_fma_f32 v[2:3], v[62:63], v[58:59], v[60:61]
	v_lshlrev_b32_e32 v60, 16, v120
	v_mul_f32_e32 v12, 0x3d372713, v60
	v_mul_f32_e32 v12, v12, v60
	v_mov_b32_e32 v16, v60
	v_fmac_f32_e32 v16, v12, v16
	v_mul_f32_e32 v12, 0x3f4c422a, v16
	v_add_f32_e32 v12, v12, v12
	v_mul_f32_e32 v12, 0x3fb8aa3b, v12
	v_exp_f32_e32 v12, v12
	v_and_b32_e32 v61, 0xffff0000, v120
	v_mov_b32_e32 v16, v61
	v_pk_mul_f32 v[122:123], v[138:139], v[10:11]
	v_add_f32_e32 v12, 1.0, v12
	v_rcp_f32_e32 v62, v12
	v_mul_f32_e32 v12, 0x3d372713, v61
	v_mul_f32_e32 v12, v12, v61
	v_fmac_f32_e32 v16, v12, v16
	v_mul_f32_e32 v12, 0x3f4c422a, v16
	v_add_f32_e32 v12, v12, v12
	v_mul_f32_e32 v12, 0x3fb8aa3b, v12
	v_exp_f32_e32 v12, v12
	v_pk_mul_f32 v[60:61], v[60:61], 0.5 op_sel_hi:[1,0]
	v_and_b32_e32 v16, 0xffff0000, v13
	v_pk_fma_f32 v[16:17], v[116:117], v[144:145], v[16:17]
	v_add_f32_e32 v12, 1.0, v12
	v_rcp_f32_e32 v63, v12
	v_pk_fma_f32 v[12:13], v[126:127], v[58:59], v[150:151]
	v_pk_mul_f32 v[58:59], v[116:117], v[170:171]
	v_exp_f32_e32 v136, v136
	v_pk_fma_f32 v[62:63], v[62:63], 2.0, 1.0 op_sel_hi:[1,0,0] neg_lo:[1,0,0] neg_hi:[1,0,0]
	v_exp_f32_e32 v137, v137
	v_pk_add_f32 v[62:63], v[62:63], 1.0 op_sel_hi:[1,0]
	v_add_f32_e32 v43, 1.0, v43
	v_pk_mul_f32 v[172:173], v[60:61], v[62:63]
	v_and_b32_e32 v63, 0xffff0000, v8
	v_and_b32_e32 v62, 0xffff0000, v4
	v_pk_fma_f32 v[138:139], v[138:139], v[130:131], v[62:63]
	v_lshlrev_b32_e32 v62, 16, v121
	v_mul_f32_e32 v4, 0x3d372713, v62
	v_mul_f32_e32 v4, v4, v62
	v_mov_b32_e32 v8, v62
	v_fmac_f32_e32 v8, v4, v8
	v_mul_f32_e32 v4, 0x3f4c422a, v8
	v_add_f32_e32 v4, v4, v4
	v_mul_f32_e32 v4, 0x3fb8aa3b, v4
	v_exp_f32_e32 v4, v4
	v_and_b32_e32 v63, 0xffff0000, v121
	v_mov_b32_e32 v8, v63
	v_pk_fma_f32 v[60:61], v[162:163], v[40:41], v[160:161]
	v_add_f32_e32 v4, 1.0, v4
	v_rcp_f32_e32 v120, v4
	v_mul_f32_e32 v4, 0x3d372713, v63
	v_mul_f32_e32 v4, v4, v63
	v_fmac_f32_e32 v8, v4, v8
	v_mul_f32_e32 v4, 0x3f4c422a, v8
	v_add_f32_e32 v4, v4, v4
	v_mul_f32_e32 v4, 0x3fb8aa3b, v4
	v_exp_f32_e32 v4, v4
	s_nop 1
	v_mov_b32_dpp v8, v16 row_shr:1 row_mask:0xf bank_mask:0xf bound_ctrl:1
	v_pk_mul_f32 v[62:63], v[62:63], 0.5 op_sel_hi:[1,0]
	v_rcp_f32_e32 v42, v42
	v_add_f32_e32 v4, 1.0, v4
	v_rcp_f32_e32 v121, v4
	s_nop 1
	v_mov_b32_dpp v4, v58 row_shr:1 row_mask:0xf bank_mask:0xf bound_ctrl:1
	s_waitcnt lgkmcnt(0)
	v_fma_f32 v8, v58, v8, v16
	v_cndmask_b32_e64 v8, v8, v16, s[38:39]
	s_nop 1
	v_mov_b32_dpp v117, v8 row_shr:2 row_mask:0xf bank_mask:0xf bound_ctrl:1
	v_pk_fma_f32 v[120:121], v[120:121], 2.0, 1.0 op_sel_hi:[1,0,0] neg_lo:[1,0,0] neg_hi:[1,0,0]
	s_waitcnt lgkmcnt(0)
	v_mul_f32_e32 v4, v58, v4
	v_cndmask_b32_e64 v4, v4, v58, s[38:39]
	s_nop 1
	v_mov_b32_dpp v116, v4 row_shr:2 row_mask:0xf bank_mask:0xf bound_ctrl:1
	s_waitcnt lgkmcnt(0)
	v_fma_f32 v117, v4, v117, v8
	v_cndmask_b32_e64 v8, v8, v117, s[40:41]
	s_nop 1
	v_mov_b32_dpp v117, v8 row_shr:4 row_mask:0xf bank_mask:0xf bound_ctrl:1
	v_pk_add_f32 v[120:121], v[120:121], 1.0 op_sel_hi:[1,0]
	s_waitcnt lgkmcnt(0)
	v_mul_f32_e32 v116, v4, v116
	v_cndmask_b32_e64 v4, v4, v116, s[40:41]
	s_nop 1
	v_mov_b32_dpp v116, v4 row_shr:4 row_mask:0xf bank_mask:0xf bound_ctrl:1
	s_waitcnt lgkmcnt(0)
	v_fma_f32 v117, v4, v117, v8
	v_cndmask_b32_e64 v8, v8, v117, s[42:43]
	s_nop 1
	v_mov_b32_dpp v117, v8 row_shr:8 row_mask:0xf bank_mask:0xf bound_ctrl:1
	v_pk_mul_f32 v[120:121], v[62:63], v[120:121]
	s_waitcnt lgkmcnt(0)
	v_mul_f32_e32 v116, v4, v116
	v_cndmask_b32_e64 v4, v4, v116, s[42:43]
	s_nop 1
	v_mov_b32_dpp v116, v4 row_shr:8 row_mask:0xf bank_mask:0xf bound_ctrl:1
	s_waitcnt lgkmcnt(0)
	v_fma_f32 v117, v4, v117, v8
	v_cndmask_b32_e64 v8, v8, v117, s[44:45]
	s_nop 1
	v_mov_b32_dpp v117, v17 row_shr:1 row_mask:0xf bank_mask:0xf bound_ctrl:1
	v_mov_b32_dpp v8, v8 row_shr:1 row_mask:0xf bank_mask:0xf
	s_waitcnt lgkmcnt(0)
	v_mul_f32_e32 v116, v4, v116
	v_cndmask_b32_e64 v4, v4, v116, s[44:45]
	s_nop 1
	v_mov_b32_dpp v116, v59 row_shr:1 row_mask:0xf bank_mask:0xf bound_ctrl:1
	s_waitcnt lgkmcnt(0)
	v_fma_f32 v117, v59, v117, v17
	v_cndmask_b32_e64 v117, v117, v17, s[38:39]
	s_nop 1
	v_mov_b32_dpp v127, v117 row_shr:2 row_mask:0xf bank_mask:0xf bound_ctrl:1
	v_mov_b32_dpp v4, v4 row_shr:1 row_mask:0xf bank_mask:0xf
	s_waitcnt lgkmcnt(0)
	v_mul_f32_e32 v116, v59, v116
	v_cndmask_b32_e64 v116, v116, v59, s[38:39]
	s_nop 1
	v_mov_b32_dpp v126, v116 row_shr:2 row_mask:0xf bank_mask:0xf bound_ctrl:1
	s_waitcnt lgkmcnt(0)
	v_fma_f32 v127, v116, v127, v117
	v_cndmask_b32_e64 v117, v117, v127, s[40:41]
	s_nop 1
	v_mov_b32_dpp v127, v117 row_shr:4 row_mask:0xf bank_mask:0xf bound_ctrl:1
	v_lshl_add_u64 v[62:63], v[106:107], 0, v[100:101]
	s_waitcnt lgkmcnt(0)
	v_mul_f32_e32 v126, v116, v126
	v_cndmask_b32_e64 v116, v116, v126, s[40:41]
	s_nop 1
	v_mov_b32_dpp v126, v116 row_shr:4 row_mask:0xf bank_mask:0xf bound_ctrl:1
	s_waitcnt lgkmcnt(0)
; __device__ __forceinline__ float bflo(unsigned w) { return __uint_as_float(w << 16); }
; __device__ __forceinline__ float bfhi(unsigned w) { return __uint_as_float(w & 0xffff0000u); }
; __device__ __forceinline__ float gelu_tanh(float x) { const float y = 0.7978845608028654f * (x + 0.044715f * x * x * x); const float e = __expf(2.0f * y); const float th = 1.0f - 2.0f * __builtin_amdgcn_rcpf(e + 1.0f); return 0.5f * x * (1.0f + th); }
; __device__ __forceinline__ void scan_final(const Args& a, int gw, int ngw, int lane, int layer) {
;     ...
;                         const float Pp = d == 0 ? __shfl_up(Pi, sft, 16) : __shfl_down(Pi, sft, 16), Hp = d == 0 ? __shfl_up(Hi, sft, 16) : __shfl_down(Hi, sft, 16);
;                         const bool has = d == 0 ? (j >= sft) : (j + sft <= 15);
;                         if (has) { Hi = Pi * Hp + Hi; Pi = Pi * Pp; }
;                     }
;                     float Pe = d == 0 ? __shfl_up(Pi, 1, 16) : __shfl_down(Pi, 1, 16), He = d == 0 ? __shfl_up(Hi, 1, 16) : __shfl_down(Hi, 1, 16);
;                     if (d == 0 ? (j == 0) : (j == 15)) { Pe = 1.f; He = 0.f; }
;                     const float c0 = __shfl(cv, eh * 4 + e + 8 * d, 16);
;                     const float sj = Pe * c0 + He;
; #pragma unroll
;                     for (int k = 0; k < 8; ++k) { const float hv = hl[k] + pl[k] * sj; if (d == 0) acc[k][e] = hv; else acc[k][e] += hv; }
;     ...
;             for (int k = 0; k < 8; ++k) { const float r0 = bflo(rgw[k].x), r1 = bfhi(rgw[k].x), r2 = bflo(rgw[k].y), r3 = bfhi(rgw[k].y);
;                 u32x2 w; w.x = pk2(acc[k][0] * gelu_tanh(r0), acc[k][1] * gelu_tanh(r1)); w.y = pk2(acc[k][2] * gelu_tanh(r2), acc[k][3] * gelu_tanh(r3));
;                 *(u32x2*)(YS + (size_t)(row0 + k) * 3072 + c4) = w; }
	v_fma_f32 v127, v116, v127, v117
	v_cndmask_b32_e64 v117, v117, v127, s[42:43]
	s_nop 1
	v_mov_b32_dpp v127, v117 row_shr:8 row_mask:0xf bank_mask:0xf bound_ctrl:1
	v_rcp_f32_e32 v43, v43
	s_waitcnt lgkmcnt(0)
	v_mul_f32_e32 v126, v116, v126
	v_cndmask_b32_e64 v116, v116, v126, s[42:43]
	s_nop 1
	v_mov_b32_dpp v126, v116 row_shr:8 row_mask:0xf bank_mask:0xf bound_ctrl:1
	s_waitcnt lgkmcnt(0)
	v_fma_f32 v127, v116, v127, v117
	v_cndmask_b32_e64 v117, v117, v127, s[44:45]
	v_add_f32_e32 v136, 1.0, v136
	v_add_f32_e32 v137, 1.0, v137
	s_waitcnt lgkmcnt(0)
	v_mul_f32_e32 v126, v116, v126
	v_cndmask_b32_e64 v116, v116, v126, s[44:45]
	s_nop 1
	v_mov_b32_dpp v116, v116 row_shr:1 row_mask:0xf bank_mask:0xf
	v_mov_b32_dpp v126, v117 row_shr:1 row_mask:0xf bank_mask:0xf bound_ctrl:1
	v_rcp_f32_e32 v136, v136
	v_rcp_f32_e32 v137, v137
	v_pk_fma_f32 v[42:43], v[42:43], 2.0, 1.0 op_sel_hi:[1,0,0] neg_lo:[1,0,0] neg_hi:[1,0,0]
	s_waitcnt lgkmcnt(0)
	v_cndmask_b32_e64 v117, v116, 1.0, s[38:39]
	v_cndmask_b32_e64 v116, v4, 1.0, s[38:39]
	s_waitcnt lgkmcnt(0)
	v_cndmask_b32_e64 v127, v126, 0, s[38:39]
	v_cndmask_b32_e64 v126, v8, 0, s[38:39]
	v_pk_fma_f32 v[116:117], v[116:117], v[124:125], v[126:127]
	v_pk_mul_f32 v[30:31], v[30:31], 0.5 op_sel_hi:[1,0]
	v_pk_fma_f32 v[110:111], v[110:111], v[116:117], v[148:149]
	v_pk_fma_f32 v[124:125], v[182:183], v[116:117], v[190:191]
	v_pk_fma_f32 v[144:145], v[170:171], v[116:117], v[144:145]
	v_pk_fma_f32 v[16:17], v[58:59], v[116:117], v[16:17]
	v_pk_add_f32 v[54:55], v[110:111], v[54:55]
	v_pk_fma_f32 v[126:127], v[202:203], v[116:117], v[204:205]
	v_pk_add_f32 v[58:59], v[124:125], v[156:157]
	v_pk_add_f32 v[2:3], v[144:145], v[2:3]
	v_pk_add_f32 v[144:145], v[16:17], v[12:13]
	v_pk_mul_f32 v[12:13], v[56:57], v[54:55]
	v_pk_fma_f32 v[148:149], v[198:199], v[116:117], v[200:201]
	v_pk_fma_f32 v[150:151], v[184:185], v[116:117], v[186:187]
	v_pk_fma_f32 v[160:161], v[164:165], v[116:117], v[166:167]
	v_pk_add_f32 v[116:117], v[126:127], v[188:189]
	v_cvt_pk_bf16_f32 v110, v12, v13
	v_pk_mul_f32 v[12:13], v[192:193], v[58:59]
	v_pk_add_f32 v[124:125], v[148:149], v[168:169]
	v_cvt_pk_bf16_f32 v58, v12, v13
	v_pk_mul_f32 v[12:13], v[206:207], v[116:117]
	v_pk_add_f32 v[126:127], v[150:151], v[158:159]
	v_cvt_pk_bf16_f32 v56, v12, v13
	v_pk_mul_f32 v[12:13], v[212:213], v[124:125]
	v_pk_mul_f32 v[2:3], v[172:173], v[2:3]
	v_pk_add_f32 v[148:149], v[160:161], v[154:155]
	v_cvt_pk_bf16_f32 v54, v12, v13
	v_pk_mul_f32 v[12:13], v[208:209], v[126:127]
	v_cvt_pk_bf16_f32 v8, v2, v3
	v_lshlrev_b32_e32 v2, 16, v104
	v_cvt_pk_bf16_f32 v16, v12, v13
	v_pk_mul_f32 v[12:13], v[194:195], v[148:149]
	v_mul_f32_e32 v4, 0x3d372713, v2
	v_cvt_pk_bf16_f32 v12, v12, v13
	v_mul_f32_e32 v4, v4, v2
	v_mov_b32_e32 v13, v2
	v_fmac_f32_e32 v13, v4, v13
	v_mul_f32_e32 v4, 0x3f4c422a, v13
	v_add_f32_e32 v4, v4, v4
	v_mul_f32_e32 v4, 0x3fb8aa3b, v4
	v_exp_f32_e32 v4, v4
	v_and_b32_e32 v3, 0xffff0000, v104
	v_mov_b32_e32 v13, v3
	v_pk_add_f32 v[42:43], v[42:43], 1.0 op_sel_hi:[1,0]
	v_add_f32_e32 v4, 1.0, v4
	v_rcp_f32_e32 v116, v4
	v_mul_f32_e32 v4, 0x3d372713, v3
	v_mul_f32_e32 v4, v4, v3
	v_fmac_f32_e32 v13, v4, v13
	v_mul_f32_e32 v4, 0x3f4c422a, v13
	v_add_f32_e32 v4, v4, v4
	v_mul_f32_e32 v4, 0x3fb8aa3b, v4
	v_exp_f32_e32 v4, v4
	v_pk_mul_f32 v[2:3], v[2:3], 0.5 op_sel_hi:[1,0]
	v_pk_fma_f32 v[142:143], v[142:143], 2.0, 1.0 op_sel_hi:[1,0,0] neg_lo:[1,0,0] neg_hi:[1,0,0]
	v_pk_mul_f32 v[42:43], v[30:31], v[42:43]
	v_add_f32_e32 v4, 1.0, v4
	v_rcp_f32_e32 v117, v4
	v_pk_mul_f32 v[64:65], v[64:65], 0.5 op_sel_hi:[1,0]
	v_pk_add_f32 v[142:143], v[142:143], 1.0 op_sel_hi:[1,0]
	v_pk_fma_f32 v[136:137], v[136:137], 2.0, 1.0 op_sel_hi:[1,0,0] neg_lo:[1,0,0] neg_hi:[1,0,0]
	v_pk_fma_f32 v[116:117], v[116:117], 2.0, 1.0 op_sel_hi:[1,0,0] neg_lo:[1,0,0] neg_hi:[1,0,0]
	v_pk_mul_f32 v[142:143], v[64:65], v[142:143]
	v_pk_add_f32 v[116:117], v[116:117], 1.0 op_sel_hi:[1,0]
	v_pk_mul_f32 v[32:33], v[32:33], 0.5 op_sel_hi:[1,0]
	v_pk_mul_f32 v[2:3], v[2:3], v[116:117]
	v_and_b32_e32 v117, 0xffff0000, v9
	v_and_b32_e32 v116, 0xffff0000, v5
	v_pk_mul_f32 v[2:3], v[2:3], v[144:145]
	v_pk_fma_f32 v[4:5], v[118:119], v[40:41], v[52:53]
	v_pk_mul_f32 v[40:41], v[112:113], v[122:123]
	v_pk_fma_f32 v[52:53], v[112:113], v[138:139], v[116:117]
	v_cvt_pk_bf16_f32 v2, v2, v3
	s_nop 1
	v_mov_b32_dpp v3, v40 row_shr:1 row_mask:0xf bank_mask:0xf bound_ctrl:1
	v_mov_b32_dpp v9, v52 row_shr:1 row_mask:0xf bank_mask:0xf bound_ctrl:1
	v_pk_add_f32 v[136:137], v[136:137], 1.0 op_sel_hi:[1,0]
	v_pk_fma_f32 v[152:153], v[152:153], 2.0, 1.0 op_sel_hi:[1,0,0] neg_lo:[1,0,0] neg_hi:[1,0,0]
	v_pk_mul_f32 v[136:137], v[32:33], v[136:137]
	s_waitcnt lgkmcnt(0)
	v_mul_f32_e32 v3, v40, v3
	s_waitcnt lgkmcnt(0)
	v_fma_f32 v9, v40, v9, v52
	v_cndmask_b32_e64 v9, v9, v52, s[38:39]
	v_cndmask_b32_e64 v3, v3, v40, s[38:39]
	s_nop 1
	v_mov_b32_dpp v13, v3 row_shr:2 row_mask:0xf bank_mask:0xf bound_ctrl:1
	v_mov_b32_dpp v17, v9 row_shr:2 row_mask:0xf bank_mask:0xf bound_ctrl:1
	v_pk_mul_f32 v[132:133], v[132:133], 0.5 op_sel_hi:[1,0]
	v_pk_add_f32 v[152:153], v[152:153], 1.0 op_sel_hi:[1,0]
	v_lshl_add_u64 v[36:37], v[106:107], 0, v[88:89]
	s_waitcnt lgkmcnt(0)
	v_mul_f32_e32 v13, v3, v13
	s_waitcnt lgkmcnt(0)
	v_fma_f32 v17, v3, v17, v9
	v_cndmask_b32_e64 v9, v9, v17, s[40:41]
	v_cndmask_b32_e64 v3, v3, v13, s[40:41]
	s_nop 1
	v_mov_b32_dpp v13, v3 row_shr:4 row_mask:0xf bank_mask:0xf bound_ctrl:1
	v_mov_b32_dpp v17, v9 row_shr:4 row_mask:0xf bank_mask:0xf bound_ctrl:1
	v_pk_mul_f32 v[152:153], v[132:133], v[152:153]
	v_lshl_add_u64 v[30:31], v[106:107], 0, v[90:91]
	v_lshl_add_u64 v[64:65], v[106:107], 0, v[92:93]
	s_waitcnt lgkmcnt(0)
; __device__ __forceinline__ float bflo(unsigned w) { return __uint_as_float(w << 16); }
; __device__ __forceinline__ float bfhi(unsigned w) { return __uint_as_float(w & 0xffff0000u); }
; __device__ __forceinline__ float gelu_tanh(float x) { const float y = 0.7978845608028654f * (x + 0.044715f * x * x * x); const float e = __expf(2.0f * y); const float th = 1.0f - 2.0f * __builtin_amdgcn_rcpf(e + 1.0f); return 0.5f * x * (1.0f + th); }
; __device__ __forceinline__ void scan_final(const Args& a, int gw, int ngw, int lane, int layer) {
;     ...
;                         const float Pp = d == 0 ? __shfl_up(Pi, sft, 16) : __shfl_down(Pi, sft, 16), Hp = d == 0 ? __shfl_up(Hi, sft, 16) : __shfl_down(Hi, sft, 16);
;                         const bool has = d == 0 ? (j >= sft) : (j + sft <= 15);
;                         if (has) { Hi = Pi * Hp + Hi; Pi = Pi * Pp; }
;                     }
;                     float Pe = d == 0 ? __shfl_up(Pi, 1, 16) : __shfl_down(Pi, 1, 16), He = d == 0 ? __shfl_up(Hi, 1, 16) : __shfl_down(Hi, 1, 16);
;                     if (d == 0 ? (j == 0) : (j == 15)) { Pe = 1.f; He = 0.f; }
;                     const float c0 = __shfl(cv, eh * 4 + e + 8 * d, 16);
;                     const float sj = Pe * c0 + He;
; #pragma unroll
;                     for (int k = 0; k < 8; ++k) { const float hv = hl[k] + pl[k] * sj; if (d == 0) acc[k][e] = hv; else acc[k][e] += hv; }
;                 }
;             }
; #pragma unroll
;             for (int k = 0; k < 8; ++k) { const float r0 = bflo(rgw[k].x), r1 = bfhi(rgw[k].x), r2 = bflo(rgw[k].y), r3 = bfhi(rgw[k].y);
;                 u32x2 w; w.x = pk2(acc[k][0] * gelu_tanh(r0), acc[k][1] * gelu_tanh(r1)); w.y = pk2(acc[k][2] * gelu_tanh(r2), acc[k][3] * gelu_tanh(r3));
;                 *(u32x2*)(YS + (size_t)(row0 + k) * 3072 + c4) = w; }
	v_mul_f32_e32 v13, v3, v13
	s_waitcnt lgkmcnt(0)
	v_fma_f32 v17, v3, v17, v9
	v_cndmask_b32_e64 v9, v9, v17, s[42:43]
	v_cndmask_b32_e64 v3, v3, v13, s[42:43]
	s_nop 1
	v_mov_b32_dpp v13, v3 row_shr:8 row_mask:0xf bank_mask:0xf bound_ctrl:1
	v_mov_b32_dpp v17, v9 row_shr:8 row_mask:0xf bank_mask:0xf bound_ctrl:1
	v_lshl_add_u64 v[32:33], v[106:107], 0, v[94:95]
	v_lshl_add_u64 v[132:133], v[106:107], 0, v[96:97]
	v_lshl_add_u64 v[14:15], v[106:107], 0, v[98:99]
	s_waitcnt lgkmcnt(0)
	v_mul_f32_e32 v13, v3, v13
	s_waitcnt lgkmcnt(0)
	v_fma_f32 v17, v3, v17, v9
	v_cndmask_b32_e64 v9, v9, v17, s[44:45]
	v_cndmask_b32_e64 v3, v3, v13, s[44:45]
	s_nop 1
	v_mov_b32_dpp v13, v41 row_shr:1 row_mask:0xf bank_mask:0xf bound_ctrl:1
	v_mov_b32_dpp v17, v53 row_shr:1 row_mask:0xf bank_mask:0xf bound_ctrl:1
	v_mov_b32_dpp v3, v3 row_shr:1 row_mask:0xf bank_mask:0xf
	v_mov_b32_dpp v9, v9 row_shr:1 row_mask:0xf bank_mask:0xf
	s_waitcnt lgkmcnt(0)
	v_mul_f32_e32 v13, v41, v13
	s_waitcnt lgkmcnt(0)
	v_fma_f32 v17, v41, v17, v53
	v_cndmask_b32_e64 v17, v17, v53, s[38:39]
	v_cndmask_b32_e64 v13, v13, v41, s[38:39]
	s_nop 1
	v_mov_b32_dpp v55, v13 row_shr:2 row_mask:0xf bank_mask:0xf bound_ctrl:1
	v_mov_b32_dpp v57, v17 row_shr:2 row_mask:0xf bank_mask:0xf bound_ctrl:1
	s_waitcnt lgkmcnt(0)
	v_cndmask_b32_e64 v112, v3, 1.0, s[38:39]
	s_waitcnt lgkmcnt(0)
	v_cndmask_b32_e64 v116, v9, 0, s[38:39]
	s_waitcnt lgkmcnt(0)
	v_mul_f32_e32 v55, v13, v55
	s_waitcnt lgkmcnt(0)
	v_fma_f32 v57, v13, v57, v17
	v_cndmask_b32_e64 v17, v17, v57, s[40:41]
	v_cndmask_b32_e64 v13, v13, v55, s[40:41]
	s_nop 1
	v_mov_b32_dpp v55, v13 row_shr:4 row_mask:0xf bank_mask:0xf bound_ctrl:1
	v_mov_b32_dpp v57, v17 row_shr:4 row_mask:0xf bank_mask:0xf bound_ctrl:1
	s_waitcnt lgkmcnt(0)
	v_mul_f32_e32 v55, v13, v55
	s_waitcnt lgkmcnt(0)
	v_fma_f32 v57, v13, v57, v17
	v_cndmask_b32_e64 v17, v17, v57, s[42:43]
	v_cndmask_b32_e64 v13, v13, v55, s[42:43]
	s_nop 1
	v_mov_b32_dpp v55, v13 row_shr:8 row_mask:0xf bank_mask:0xf bound_ctrl:1
	v_mov_b32_dpp v57, v17 row_shr:8 row_mask:0xf bank_mask:0xf bound_ctrl:1
	s_waitcnt lgkmcnt(0)
	v_mul_f32_e32 v55, v13, v55
	s_waitcnt lgkmcnt(0)
	v_fma_f32 v57, v13, v57, v17
	v_cndmask_b32_e64 v17, v17, v57, s[44:45]
	v_cndmask_b32_e64 v13, v13, v55, s[44:45]
	s_nop 1
	v_mov_b32_dpp v13, v13 row_shr:1 row_mask:0xf bank_mask:0xf
	v_mov_b32_dpp v17, v17 row_shr:1 row_mask:0xf bank_mask:0xf
	s_waitcnt lgkmcnt(0)
	v_cndmask_b32_e64 v113, v13, 1.0, s[38:39]
	s_waitcnt lgkmcnt(0)
	v_cndmask_b32_e64 v117, v17, 0, s[38:39]
	v_pk_fma_f32 v[112:113], v[112:113], v[114:115], v[116:117]
	s_nop 0
	v_pk_fma_f32 v[10:11], v[10:11], v[112:113], v[130:131]
	v_pk_fma_f32 v[22:23], v[22:23], v[112:113], v[26:27]
	v_pk_fma_f32 v[26:27], v[46:47], v[112:113], v[48:49]
	v_pk_fma_f32 v[46:47], v[122:123], v[112:113], v[138:139]
	v_pk_add_f32 v[6:7], v[10:11], v[6:7]
	v_pk_add_f32 v[10:11], v[46:47], v[60:61]
	v_pk_mul_f32 v[6:7], v[128:129], v[6:7]
	v_pk_add_f32 v[18:19], v[22:23], v[18:19]
	v_cvt_pk_bf16_f32 v13, v6, v7
	v_pk_mul_f32 v[6:7], v[120:121], v[10:11]
	v_pk_fma_f32 v[24:25], v[24:25], v[112:113], v[28:29]
	v_cvt_pk_bf16_f32 v9, v6, v7
	v_lshlrev_b32_e32 v6, 16, v105
	v_mul_f32_e32 v3, 0x3d372713, v6
	global_store_dwordx2 v[62:63], v[8:9], off
	v_mul_f32_e32 v3, v3, v6
	v_mov_b32_e32 v8, v6
	v_fmac_f32_e32 v8, v3, v8
	v_mul_f32_e32 v3, 0x3f4c422a, v8
	v_add_f32_e32 v3, v3, v3
	v_mul_f32_e32 v3, 0x3fb8aa3b, v3
	v_exp_f32_e32 v3, v3
	v_and_b32_e32 v7, 0xffff0000, v105
	v_mov_b32_e32 v9, v7
	v_pk_add_f32 v[22:23], v[26:27], v[44:45]
	v_add_f32_e32 v3, 1.0, v3
	v_rcp_f32_e32 v8, v3
	v_mul_f32_e32 v3, 0x3d372713, v7
	v_mul_f32_e32 v3, v3, v7
	v_fmac_f32_e32 v9, v3, v9
	v_mul_f32_e32 v3, 0x3f4c422a, v9
	v_add_f32_e32 v3, v3, v3
	v_mul_f32_e32 v3, 0x3fb8aa3b, v3
	v_exp_f32_e32 v3, v3
	v_pk_mul_f32 v[18:19], v[42:43], v[18:19]
	v_pk_fma_f32 v[50:51], v[108:109], v[112:113], v[50:51]
	v_pk_fma_f32 v[28:29], v[140:141], v[112:113], v[146:147]
	v_add_f32_e32 v3, 1.0, v3
	v_rcp_f32_e32 v9, v3
	v_pk_fma_f32 v[40:41], v[40:41], v[112:113], v[52:53]
	v_pk_add_f32 v[20:21], v[24:25], v[20:21]
	v_cvt_pk_bf16_f32 v59, v18, v19
	v_pk_fma_f32 v[8:9], v[8:9], 2.0, 1.0 op_sel_hi:[1,0,0] neg_lo:[1,0,0] neg_hi:[1,0,0]
	v_pk_mul_f32 v[18:19], v[142:143], v[22:23]
	v_pk_mul_f32 v[6:7], v[6:7], 0.5 op_sel_hi:[1,0]
	v_pk_add_f32 v[8:9], v[8:9], 1.0 op_sel_hi:[1,0]
	v_pk_add_f32 v[34:35], v[50:51], v[34:35]
	v_pk_add_f32 v[24:25], v[28:29], v[134:135]
	v_pk_add_f32 v[4:5], v[40:41], v[4:5]
	v_cvt_pk_bf16_f32 v57, v18, v19
	v_pk_mul_f32 v[18:19], v[136:137], v[20:21]
	v_pk_mul_f32 v[6:7], v[6:7], v[8:9]
	v_pk_mul_f32 v[26:27], v[38:39], v[34:35]
	v_cvt_pk_bf16_f32 v55, v18, v19
	v_pk_mul_f32 v[18:19], v[152:153], v[24:25]
	v_pk_mul_f32 v[4:5], v[6:7], v[4:5]
	v_cvt_pk_bf16_f32 v111, v26, v27
	v_cvt_pk_bf16_f32 v17, v18, v19
	v_cvt_pk_bf16_f32 v3, v4, v5
	v_lshl_add_u64 v[4:5], v[106:107], 0, v[102:103]
	global_store_dwordx2 v[36:37], v[110:111], off
	global_store_dwordx2 v[30:31], v[58:59], off
	global_store_dwordx2 v[64:65], v[56:57], off
	global_store_dwordx2 v[32:33], v[54:55], off
	global_store_dwordx2 v[132:133], v[16:17], off
	global_store_dwordx2 v[14:15], v[12:13], off
	global_store_dwordx2 v[4:5], v[2:3], off
	s_cbranch_scc0 .LBB0_1189
	s_add_i32 s66, s66, 1
	s_cmp_eq_u32 s66, s65
	s_cbranch_scc0 .LBB0_1188
